# serial memory round trips removed in latency-bound item code: phase-2 history-row loads issued back to back, phase-2 and sample conv-state tail copy loops unrolled (loads together, one wait), dn_a_log
# baseline (speedup 1.0000x reference)
.LBB0_186:
	s_and_b32 s68, s2, 31
	s_ashr_i32 s66, s2, 7
	s_lshl_b32 s0, s68, 6
	s_lshl_b32 s1, s66, 11
	s_bfe_u32 s3, s2, 0x20005
	s_or_b32 s67, s1, s0
	s_barrier
	s_and_saveexec_b64 s[0:1], s[76:77]
	s_cbranch_execz .LBB0_190
	v_or_b32_e32 v2, s67, v0
	v_ashrrev_i32_e32 v3, 31, v2
	v_readlane_b32 s4, v237, 59
	v_lshlrev_b64 v[2:3], 5, v[2:3]
	v_readlane_b32 s5, v237, 60
	s_lshl_b32 s26, s3, 2
	s_mov_b32 s38, 0x41a00000
	v_lshl_add_u64 v[2:3], s[4:5], 0, v[2:3]
	v_lshl_add_u64 v[4:5], v[2:3], 0, s[26:27]
	v_readlane_b32 s4, v237, 35
	global_load_dword v2, v[4:5], off
	global_load_dword v3, v[4:5], off offset:16
	v_mov_b32_e32 v4, s26
	v_readlane_b32 s5, v237, 36
	v_readlane_b32 s6, v237, 37
	v_readlane_b32 s7, v237, 38
	v_readlane_b32 s8, v237, 39
	v_readlane_b32 s9, v237, 40
	v_readlane_b32 s10, v237, 41
	global_load_dword v4, v4, s[4:5]
	v_readlane_b32 s100, v237, 33
	v_readlane_b32 s101, v237, 34
	v_mov_b32_e32 v101, s26
	v_readlane_b32 s11, v237, 42
	v_readlane_b32 s12, v237, 43
	v_readlane_b32 s13, v237, 44
	v_readlane_b32 s14, v237, 45
	v_readlane_b32 s15, v237, 46
	v_readlane_b32 s16, v237, 47
	v_readlane_b32 s17, v237, 48
	v_readlane_b32 s18, v237, 49
	v_readlane_b32 s19, v237, 50
	global_load_dword v100, v101, s[100:101]
	s_waitcnt vmcnt(0)
	v_add_f32_e32 v3, v3, v4
	v_cmp_nlt_f32_e32 vcc, s38, v3
	s_and_saveexec_b64 s[38:39], vcc
	s_cbranch_execz .LBB0_189
	v_mul_f32_e32 v4, 0x3fb8aa3b, v3
	v_rndne_f32_e32 v5, v4
	v_sub_f32_e32 v6, v4, v5
	v_fma_f32 v4, v3, s61, -v4
	v_fmac_f32_e32 v4, 0x32a5705f, v3
	v_add_f32_e32 v4, v6, v4
	v_cvt_i32_f32_e32 v5, v5
	v_exp_f32_e32 v4, v4
	v_cmp_ngt_f32_e32 vcc, s62, v3
	s_mov_b32 s54, 0x3f2aaaab
	v_ldexp_f32 v4, v4, v5
	v_cndmask_b32_e32 v4, 0, v4, vcc
	v_cmp_nlt_f32_e32 vcc, s63, v3
	s_nop 1
	v_cndmask_b32_e32 v3, v190, v4, vcc
	v_add_f32_e32 v6, 1.0, v3
	v_add_f32_e32 v4, -1.0, v6
	v_sub_f32_e32 v5, v4, v6
	v_add_f32_e32 v5, 1.0, v5
	v_sub_f32_e32 v4, v3, v4
	v_add_f32_e32 v7, v4, v5
	v_frexp_mant_f32_e32 v8, v6
	v_cvt_f64_f32_e32 v[4:5], v6
	v_frexp_exp_i32_f64_e32 v4, v[4:5]
	v_cmp_gt_f32_e32 vcc, s54, v8
	s_mov_b32 s54, 0x3f317218
	s_nop 0
	v_subbrev_co_u32_e32 v12, vcc, 0, v4, vcc
	v_sub_u32_e32 v4, 0, v12
	v_ldexp_f32 v5, v6, v4
	v_add_f32_e32 v6, -1.0, v5
	v_add_f32_e32 v8, 1.0, v5
	v_ldexp_f32 v4, v7, v4
	v_add_f32_e32 v7, 1.0, v6
	v_add_f32_e32 v9, -1.0, v8
	v_sub_f32_e32 v7, v5, v7
	v_sub_f32_e32 v5, v5, v9
	v_add_f32_e32 v7, v4, v7
	v_add_f32_e32 v4, v4, v5
	v_add_f32_e32 v13, v8, v4
	v_rcp_f32_e32 v15, v13
	v_sub_f32_e32 v5, v8, v13
	v_add_f32_e32 v14, v4, v5
	v_add_f32_e32 v5, v6, v7
	v_mul_f32_e32 v17, v5, v15
	v_sub_f32_e32 v4, v6, v5
	v_mul_f32_e32 v6, v13, v17
	v_fma_f32 v8, v17, v13, -v6
	v_fmac_f32_e32 v8, v17, v14
	v_add_f32_e32 v16, v7, v4
	v_add_f32_e32 v4, v6, v8
	v_sub_f32_e32 v7, v5, v4
	v_pk_add_f32 v[10:11], v[4:5], v[6:7] neg_lo:[0,1] neg_hi:[0,1]
	v_mov_b32_e32 v9, v4
	v_pk_add_f32 v[4:5], v[10:11], v[8:9] neg_lo:[0,1] neg_hi:[0,1]
	s_nop 0
	v_add_f32_e32 v5, v16, v5
	v_add_f32_e32 v4, v4, v5
	v_add_f32_e32 v5, v7, v4
	v_mul_f32_e32 v16, v15, v5
	v_mul_f32_e32 v6, v13, v16
	v_fma_f32 v8, v16, v13, -v6
	v_fmac_f32_e32 v8, v16, v14
	v_sub_f32_e32 v7, v7, v5
	v_add_f32_e32 v13, v4, v7
	v_add_f32_e32 v4, v6, v8
	v_sub_f32_e32 v7, v5, v4
	v_pk_add_f32 v[10:11], v[4:5], v[6:7] neg_lo:[0,1] neg_hi:[0,1]
	v_mov_b32_e32 v9, v4
	v_pk_add_f32 v[4:5], v[10:11], v[8:9] neg_lo:[0,1] neg_hi:[0,1]
	s_nop 0
	v_add_f32_e32 v5, v13, v5
	v_add_f32_e32 v4, v4, v5
	v_add_f32_e32 v5, v17, v16
	v_add_f32_e32 v4, v7, v4
	v_sub_f32_e32 v6, v5, v17
	v_mul_f32_e32 v4, v15, v4
	v_sub_f32_e32 v6, v16, v6
	v_add_f32_e32 v6, v6, v4
	v_add_f32_e32 v8, v5, v6
	v_mul_f32_e32 v9, v8, v8
	v_fmamk_f32 v4, v9, 0x3e9b6dac, v173
	v_fmaak_f32 v81, v9, v4, 0x3f2aaada
	v_cvt_f32_i32_e32 v4, v12
	v_sub_f32_e32 v5, v8, v5
	v_sub_f32_e32 v5, v6, v5
	v_ldexp_f32 v10, v5, 1
	v_mul_f32_e32 v5, v8, v9
	v_ldexp_f32 v7, v8, 1
	v_pk_mul_f32 v[8:9], v[4:5], v[80:81]
	s_nop 0
	v_fma_f32 v6, v4, s54, -v8
	v_fmac_f32_e32 v6, 0xb102e308, v4
	v_pk_add_f32 v[4:5], v[8:9], v[6:7]
	s_mov_b32 s54, 0x7f800000
	v_sub_f32_e32 v7, v5, v7
	v_sub_f32_e32 v7, v9, v7
	v_add_f32_e32 v11, v10, v7
	v_mov_b32_e32 v10, v8
	v_pk_add_f32 v[8:9], v[4:5], v[8:9] neg_lo:[0,1] neg_hi:[0,1]
	v_pk_add_f32 v[12:13], v[4:5], v[10:11]
	v_mov_b32_e32 v7, v4
	v_mov_b32_e32 v9, v13
	v_pk_add_f32 v[14:15], v[6:7], v[8:9] neg_lo:[0,1] neg_hi:[0,1]
	v_pk_add_f32 v[6:7], v[6:7], v[8:9]
	v_mov_b32_e32 v10, v11
	v_pk_add_f32 v[8:9], v[6:7], v[4:5] op_sel:[1,0] op_sel_hi:[0,1] neg_lo:[0,1] neg_hi:[0,1]
	v_pk_add_f32 v[16:17], v[12:13], v[8:9] op_sel_hi:[1,0] neg_lo:[0,1] neg_hi:[0,1]
	v_mov_b32_e32 v12, v13
	v_mov_b32_e32 v13, v7
	v_pk_mov_b32 v[8:9], v[4:5], v[8:9] op_sel:[1,0]
	v_mov_b32_e32 v11, v4
	v_pk_add_f32 v[8:9], v[12:13], v[8:9] neg_lo:[0,1] neg_hi:[0,1]
	v_mov_b32_e32 v16, v14
	v_pk_add_f32 v[4:5], v[10:11], v[8:9] neg_lo:[0,1] neg_hi:[0,1]
	v_mov_b32_e32 v15, v7
	v_pk_add_f32 v[8:9], v[16:17], v[4:5]
	v_cmp_neq_f32_e32 vcc, s54, v3
	v_pk_add_f32 v[10:11], v[8:9], v[8:9] op_sel:[0,1] op_sel_hi:[1,0]
	s_mov_b32 s54, 0x33800000
	v_pk_add_f32 v[6:7], v[6:7], v[10:11] op_sel:[1,0] op_sel_hi:[0,1]
	v_mov_b32_e32 v9, v6
	v_pk_add_f32 v[12:13], v[8:9], v[14:15] neg_lo:[0,1] neg_hi:[0,1]
	v_mov_b32_e32 v5, v10
	v_sub_f32_e32 v7, v8, v12
	v_pk_add_f32 v[4:5], v[4:5], v[12:13] neg_lo:[0,1] neg_hi:[0,1]
	v_sub_f32_e32 v7, v14, v7
	v_add_f32_e32 v4, v4, v7
	v_add_f32_e32 v4, v4, v5
	v_add_f32_e32 v4, v6, v4
	v_cndmask_b32_e32 v4, v190, v4, vcc
	v_cmp_lt_f32_e64 vcc, |v3|, s54
	s_nop 1
	v_cndmask_b32_e32 v3, v4, v3, vcc
.LBB0_189:
	s_or_b64 exec, exec, s[38:39]
	v_readlane_b32 s4, v237, 19
	v_mov_b32_e32 v4, s26
	v_readlane_b32 s18, v237, 33
	v_readlane_b32 s19, v237, 34
	v_mul_f32_e32 v2, 0xbfb8aa3b, v2
	v_exp_f32_e32 v2, v2
	v_readlane_b32 s5, v237, 20
	v_readlane_b32 s6, v237, 21
	v_readlane_b32 s7, v237, 22
	v_mov_b32_e32 v4, v100
	v_add_f32_e32 v2, 1.0, v2
	v_rcp_f32_e32 v2, v2
	v_readlane_b32 s8, v237, 23
	v_readlane_b32 s9, v237, 24
	v_readlane_b32 s10, v237, 25
	v_readlane_b32 s11, v237, 26
	v_readlane_b32 s12, v237, 27
	v_readlane_b32 s13, v237, 28
	v_readlane_b32 s14, v237, 29
	v_readlane_b32 s15, v237, 30
	v_readlane_b32 s16, v237, 31
	v_readlane_b32 s17, v237, 32
	s_waitcnt vmcnt(0)
	v_mul_f32_e32 v5, 0x3fb8aa3b, v4
	v_fma_f32 v6, v4, s61, -v5
	v_rndne_f32_e32 v7, v5
	v_fmac_f32_e32 v6, 0x32a5705f, v4
	v_sub_f32_e32 v5, v5, v7
	v_add_f32_e32 v5, v5, v6
	v_cvt_i32_f32_e32 v7, v7
	v_exp_f32_e32 v5, v5
	v_cmp_ngt_f32_e32 vcc, s62, v4
	v_ldexp_f32 v5, v5, v7
	s_nop 0
	v_cndmask_b32_e32 v5, 0, v5, vcc
	v_cmp_nlt_f32_e32 vcc, s63, v4
	s_nop 1
	v_cndmask_b32_e32 v4, v190, v5, vcc
	v_mul_f32_e64 v5, v3, -v4
	ds_bpermute_b32 v6, v163, v5
	s_waitcnt lgkmcnt(0)
	v_fma_f32 v3, v3, -v4, v6
	v_cndmask_b32_e64 v3, v3, v5, s[36:37]
	ds_bpermute_b32 v4, v164, v3
	s_waitcnt lgkmcnt(0)
	v_add_f32_e32 v4, v3, v4
	v_cndmask_b32_e64 v3, v4, v3, s[88:89]
	ds_bpermute_b32 v4, v165, v3
	s_waitcnt lgkmcnt(0)
	v_add_f32_e32 v4, v3, v4
	v_cndmask_b32_e64 v3, v4, v3, s[96:97]
	ds_bpermute_b32 v4, v166, v3
	s_waitcnt lgkmcnt(0)
	v_add_f32_e32 v4, v3, v4
	v_cndmask_b32_e64 v3, v4, v3, s[40:41]
	ds_bpermute_b32 v4, v167, v3
	s_waitcnt lgkmcnt(0)
	v_add_f32_e32 v4, v3, v4
	v_cndmask_b32_e64 v3, v4, v3, s[42:43]
	ds_bpermute_b32 v4, v168, v3
	s_waitcnt lgkmcnt(0)
	v_add_f32_e32 v4, v3, v4
	v_cndmask_b32_e64 v4, v4, v3, s[52:53]
	ds_bpermute_b32 v5, v169, v4
	s_waitcnt lgkmcnt(0)
	v_sub_f32_e32 v4, v4, v5
	v_cndmask_b32_e64 v3, v3, v4, s[48:49]
	ds_write2st64_b32 v109, v3, v2 offset0:200 offset1:201

.LBB0_276:
	s_andn2_saveexec_b64 s[54:55], s[0:1]
	s_cbranch_execz .LBB0_285
	v_or_b32_e32 v2, s26, v0
	v_or_b32_e32 v6, 0x400, v2
	v_readlane_b32 s4, v237, 19
	v_lshlrev_b32_e32 v3, 2, v6
	v_readlane_b32 s16, v237, 31
	v_readlane_b32 s17, v237, 32
	v_lshlrev_b32_e32 v70, 2, v2
	s_cmp_lg_u32 s68, 0
	s_cselect_b64 s[56:57], -1, 0
	s_cmp_eq_u32 s68, 0
	v_readlane_b32 s5, v237, 20
	global_load_dword v106, v3, s[16:17]
	v_lshl_add_u64 v[2:3], s[16:17], 0, v[70:71]
	v_add_co_u32_e32 v4, vcc, 0x2000, v2
	v_lshlrev_b32_e32 v70, 1, v6
	s_nop 0
	v_addc_co_u32_e32 v5, vcc, 0, v3, vcc
	global_load_dword v108, v[4:5], off offset:2048
	v_add_co_u32_e32 v4, vcc, 0x4000, v2
	v_readlane_b32 s6, v237, 21
	s_nop 0
	v_addc_co_u32_e32 v5, vcc, 0, v3, vcc
	v_add_co_u32_e32 v2, vcc, 0x5000, v2
	global_load_dword v110, v[4:5], off
	s_nop 0
	v_addc_co_u32_e32 v3, vcc, 0, v3, vcc
	global_load_dword v112, v[2:3], off offset:2048
	v_mov_b32_e32 v3, 0
	v_mov_b32_e32 v2, 0
	v_readlane_b32 s7, v237, 22
	v_readlane_b32 s8, v237, 23
	v_readlane_b32 s9, v237, 24
	v_readlane_b32 s10, v237, 25
	v_readlane_b32 s11, v237, 26
	v_readlane_b32 s12, v237, 27
	v_readlane_b32 s13, v237, 28
	v_readlane_b32 s14, v237, 29
	v_readlane_b32 s15, v237, 30
	v_readlane_b32 s18, v237, 33
	v_readlane_b32 s19, v237, 34
	s_cbranch_scc1 .LBB0_279
	s_add_i32 s0, s67, -3
	s_mul_hi_i32 s1, s0, 0x1c00
	s_mulk_i32 s0, 0x1c00
	s_add_u32 s0, s74, s0
	s_addc_u32 s1, s75, s1
	global_load_ushort v2, v70, s[0:1] offset:3072
.LBB0_279:
	v_cndmask_b32_e64 v4, 0, 1, s[56:57]
	v_cmp_ne_u32_e64 s[0:1], 1, v4
	s_andn2_b64 vcc, exec, s[56:57]
	s_cbranch_vccnz .LBB0_281
	s_add_i32 s56, s67, -2
	s_mul_hi_i32 s57, s56, 0x1c00
	s_mulk_i32 s56, 0x1c00
	s_add_u32 s56, s74, s56
	s_addc_u32 s57, s75, s57
	global_load_ushort v3, v70, s[56:57] offset:3072
.LBB0_281:
	s_and_b64 vcc, exec, s[0:1]
	s_cbranch_vccnz .LBB0_283
	s_add_i32 s0, s67, -1
	s_mul_hi_i32 s1, s0, 0x1c00
	s_mulk_i32 s0, 0x1c00
	s_add_u32 s0, s74, s0
	s_addc_u32 s1, s75, s1
	global_load_ushort v4, v70, s[0:1] offset:3072
	s_branch .LBB0_284
.LBB0_283:
	v_mov_b32_e32 v4, 0
.LBB0_284:
	s_waitcnt vmcnt(0)
	v_lshlrev_b32_e32 v2, 16, v2
	v_lshlrev_b32_e32 v3, 16, v3
	v_lshlrev_b32_e32 v61, 16, v4
	s_mul_i32 s0, s67, 0x1c00
	s_mul_hi_i32 s1, s67, 0x1c00
	s_add_u32 s0, s74, s0
	s_addc_u32 s1, s75, s1
	v_lshl_add_u64 v[4:5], s[0:1], 0, v[70:71]
	global_load_ushort v7, v70, s[0:1] offset:3072
	s_mov_b32 s0, 0x68000
	v_add_co_u32_e32 v8, vcc, s0, v4
	s_mov_b32 s0, 0x69000
	s_nop 0
	v_addc_co_u32_e32 v9, vcc, 0, v5, vcc
	global_load_ushort v6, v[8:9], off
	v_add_co_u32_e32 v8, vcc, s0, v4
	s_mov_b32 s0, 0x6b000
	s_nop 0
	v_addc_co_u32_e32 v9, vcc, 0, v5, vcc
	v_add_co_u32_e32 v10, vcc, s0, v4
	s_mov_b32 s0, 0x6d000
	s_nop 0
	v_addc_co_u32_e32 v11, vcc, 0, v5, vcc
	global_load_ushort v8, v[8:9], off offset:3072
	s_waitcnt vmcnt(2)
	v_lshlrev_b32_e32 v63, 16, v7
	global_load_ushort v9, v[10:11], off offset:2048
	v_add_co_u32_e32 v10, vcc, s0, v4
	s_mov_b32 s0, 0x6f000
	s_nop 0
	v_addc_co_u32_e32 v11, vcc, 0, v5, vcc
	v_add_co_u32_e32 v12, vcc, s0, v4
	s_mov_b32 s0, 0x64000
	s_nop 0
	v_addc_co_u32_e32 v13, vcc, 0, v5, vcc
	global_load_ushort v10, v[10:11], off offset:1024
	s_nop 0
	global_load_ushort v11, v[12:13], off
	v_add_co_u32_e32 v12, vcc, s0, v4
	s_mov_b32 s0, 0x66000
	s_nop 0
	v_addc_co_u32_e32 v13, vcc, 0, v5, vcc
	v_add_co_u32_e32 v14, vcc, s0, v4
	s_mov_b32 s0, 0x61000
	s_nop 0
	v_addc_co_u32_e32 v15, vcc, 0, v5, vcc
	global_load_ushort v12, v[12:13], off offset:2048
	s_nop 0
	global_load_ushort v13, v[14:15], off offset:1024
	v_add_co_u32_e32 v14, vcc, s0, v4
	s_mov_b32 s0, 0x62000
	s_nop 0
	v_addc_co_u32_e32 v15, vcc, 0, v5, vcc
	v_add_co_u32_e32 v16, vcc, s0, v4
	s_mov_b32 s0, 0x5d000
	s_nop 0
	v_addc_co_u32_e32 v17, vcc, 0, v5, vcc
	global_load_ushort v14, v[14:15], off
	s_nop 0
	global_load_ushort v15, v[16:17], off offset:3072
	v_add_co_u32_e32 v16, vcc, s0, v4
	s_mov_b32 s0, 0x5f000
	s_nop 0
	v_addc_co_u32_e32 v17, vcc, 0, v5, vcc
	v_add_co_u32_e32 v18, vcc, s0, v4
	s_mov_b32 s0, 0x5a000
	s_nop 0
	v_addc_co_u32_e32 v19, vcc, 0, v5, vcc
	global_load_ushort v16, v[16:17], off offset:2048
	s_nop 0
	global_load_ushort v17, v[18:19], off offset:1024
	v_add_co_u32_e32 v18, vcc, s0, v4
	s_mov_b32 s0, 0x5b000
	s_nop 0
	v_addc_co_u32_e32 v19, vcc, 0, v5, vcc
	v_add_co_u32_e32 v20, vcc, s0, v4
	s_mov_b32 s0, 0x56000
	s_nop 0
	v_addc_co_u32_e32 v21, vcc, 0, v5, vcc
	global_load_ushort v18, v[18:19], off
	s_nop 0
	global_load_ushort v19, v[20:21], off offset:3072
	v_add_co_u32_e32 v20, vcc, s0, v4
	s_mov_b32 s0, 0x58000
	s_nop 0
	v_addc_co_u32_e32 v21, vcc, 0, v5, vcc
	v_add_co_u32_e32 v22, vcc, s0, v4
	s_mov_b32 s0, 0x53000
	s_nop 0
	v_addc_co_u32_e32 v23, vcc, 0, v5, vcc
	global_load_ushort v20, v[20:21], off offset:2048
	s_nop 0
	global_load_ushort v21, v[22:23], off offset:1024
	v_add_co_u32_e32 v22, vcc, s0, v4
	s_mov_b32 s0, 0x54000
	s_nop 0
	v_addc_co_u32_e32 v23, vcc, 0, v5, vcc
	v_add_co_u32_e32 v24, vcc, s0, v4
	s_mov_b32 s0, 0x4f000
	s_nop 0
	v_addc_co_u32_e32 v25, vcc, 0, v5, vcc
	global_load_ushort v22, v[22:23], off
	s_nop 0
	global_load_ushort v23, v[24:25], off offset:3072
	v_add_co_u32_e32 v24, vcc, s0, v4
	s_mov_b32 s0, 0x51000
	s_nop 0
	v_addc_co_u32_e32 v25, vcc, 0, v5, vcc
	v_add_co_u32_e32 v26, vcc, s0, v4
	s_mov_b32 s0, 0x4c000
	s_nop 0
	v_addc_co_u32_e32 v27, vcc, 0, v5, vcc
	global_load_ushort v24, v[24:25], off offset:2048
	s_nop 0
	global_load_ushort v25, v[26:27], off offset:1024
	v_add_co_u32_e32 v26, vcc, s0, v4
	s_mov_b32 s0, 0x4d000
	s_nop 0
	v_addc_co_u32_e32 v27, vcc, 0, v5, vcc
	v_add_co_u32_e32 v28, vcc, s0, v4
	s_mov_b32 s0, 0x48000
	s_nop 0
	v_addc_co_u32_e32 v29, vcc, 0, v5, vcc
	global_load_ushort v26, v[26:27], off
	s_nop 0
	global_load_ushort v27, v[28:29], off offset:3072
	v_add_co_u32_e32 v28, vcc, s0, v4
	s_mov_b32 s0, 0x4a000
	s_nop 0
	v_addc_co_u32_e32 v29, vcc, 0, v5, vcc
	v_add_co_u32_e32 v30, vcc, s0, v4
	s_mov_b32 s0, 0x45000
	s_nop 0
	v_addc_co_u32_e32 v31, vcc, 0, v5, vcc
	global_load_ushort v28, v[28:29], off offset:2048
	s_nop 0
	global_load_ushort v29, v[30:31], off offset:1024
	v_add_co_u32_e32 v30, vcc, s0, v4
	s_mov_b32 s0, 0x46000
	s_nop 0
	v_addc_co_u32_e32 v31, vcc, 0, v5, vcc
	v_add_co_u32_e32 v32, vcc, s0, v4
	s_mov_b32 s0, 0x41000
	s_nop 0
	v_addc_co_u32_e32 v33, vcc, 0, v5, vcc
	global_load_ushort v30, v[30:31], off
	s_nop 0
	global_load_ushort v31, v[32:33], off offset:3072
	v_add_co_u32_e32 v32, vcc, s0, v4
	s_mov_b32 s0, 0x43000
	s_nop 0
	v_addc_co_u32_e32 v33, vcc, 0, v5, vcc
	v_add_co_u32_e32 v34, vcc, s0, v4
	s_mov_b32 s0, 0x3e000
	s_nop 0
	v_addc_co_u32_e32 v35, vcc, 0, v5, vcc
	global_load_ushort v32, v[32:33], off offset:2048
	s_nop 0
	global_load_ushort v33, v[34:35], off offset:1024
	v_add_co_u32_e32 v34, vcc, s0, v4
	s_mov_b32 s0, 0x3f000
	s_nop 0
	v_addc_co_u32_e32 v35, vcc, 0, v5, vcc
	global_load_ushort v36, v[34:35], off
	v_add_co_u32_e32 v34, vcc, s0, v4
	s_mov_b32 s0, 0x3a000
	s_nop 0
	v_addc_co_u32_e32 v35, vcc, 0, v5, vcc
	global_load_ushort v37, v[34:35], off offset:3072
	v_add_co_u32_e32 v34, vcc, s0, v4
	s_mov_b32 s0, 0x3c000
	s_nop 0
	v_addc_co_u32_e32 v35, vcc, 0, v5, vcc
	global_load_ushort v38, v[34:35], off offset:2048
	v_add_co_u32_e32 v34, vcc, s0, v4
	s_mov_b32 s0, 0x37000
	s_nop 0
	v_addc_co_u32_e32 v35, vcc, 0, v5, vcc
	global_load_ushort v39, v[34:35], off offset:1024
	v_add_co_u32_e32 v34, vcc, s0, v4
	s_mov_b32 s0, 0x38000
	s_nop 0
	v_addc_co_u32_e32 v35, vcc, 0, v5, vcc
	global_load_ushort v40, v[34:35], off
	v_add_co_u32_e32 v34, vcc, s0, v4
	s_mov_b32 s0, 0x33000
	s_nop 0
	v_addc_co_u32_e32 v35, vcc, 0, v5, vcc
	global_load_ushort v41, v[34:35], off offset:3072
	v_add_co_u32_e32 v34, vcc, s0, v4
	s_mov_b32 s0, 0x35000
	s_nop 0
	v_addc_co_u32_e32 v35, vcc, 0, v5, vcc
	global_load_ushort v42, v[34:35], off offset:2048
	v_add_co_u32_e32 v34, vcc, s0, v4
	s_mov_b32 s0, 0x30000
	s_nop 0
	v_addc_co_u32_e32 v35, vcc, 0, v5, vcc
	global_load_ushort v43, v[34:35], off offset:1024
	v_add_co_u32_e32 v34, vcc, s0, v4
	s_mov_b32 s0, 0x31000
	s_nop 0
	v_addc_co_u32_e32 v35, vcc, 0, v5, vcc
	global_load_ushort v44, v[34:35], off
	v_add_co_u32_e32 v34, vcc, s0, v4
	s_mov_b32 s0, 0x2c000
	s_nop 0
	v_addc_co_u32_e32 v35, vcc, 0, v5, vcc
	global_load_ushort v45, v[34:35], off offset:3072
	v_add_co_u32_e32 v34, vcc, s0, v4
	s_mov_b32 s0, 0x2e000
	s_nop 0
	v_addc_co_u32_e32 v35, vcc, 0, v5, vcc
	global_load_ushort v46, v[34:35], off offset:2048
	v_add_co_u32_e32 v34, vcc, s0, v4
	s_mov_b32 s0, 0x29000
	s_nop 0
	v_addc_co_u32_e32 v35, vcc, 0, v5, vcc
	global_load_ushort v47, v[34:35], off offset:1024
	v_add_co_u32_e32 v34, vcc, s0, v4
	s_mov_b32 s0, 0x2a000
	s_nop 0
	v_addc_co_u32_e32 v35, vcc, 0, v5, vcc
	global_load_ushort v48, v[34:35], off
	v_add_co_u32_e32 v34, vcc, s0, v4
	s_mov_b32 s0, 0x25000
	s_nop 0
	v_addc_co_u32_e32 v35, vcc, 0, v5, vcc
	global_load_ushort v49, v[34:35], off offset:3072
	v_add_co_u32_e32 v34, vcc, s0, v4
	s_mov_b32 s0, 0x27000
	s_nop 0
	v_addc_co_u32_e32 v35, vcc, 0, v5, vcc
	global_load_ushort v50, v[34:35], off offset:2048
	v_add_co_u32_e32 v34, vcc, s0, v4
	s_mov_b32 s0, 0x22000
	s_nop 0
	v_addc_co_u32_e32 v35, vcc, 0, v5, vcc
	global_load_ushort v51, v[34:35], off offset:1024
	v_add_co_u32_e32 v34, vcc, s0, v4
	s_mov_b32 s0, 0x23000
	s_nop 0
	v_addc_co_u32_e32 v35, vcc, 0, v5, vcc
	global_load_ushort v52, v[34:35], off
	v_add_co_u32_e32 v34, vcc, s0, v4
	s_mov_b32 s0, 0x1e000
	s_nop 0
	v_addc_co_u32_e32 v35, vcc, 0, v5, vcc
	global_load_ushort v53, v[34:35], off offset:3072
	v_add_co_u32_e32 v34, vcc, s0, v4
	s_mov_b32 s0, 0x20000
	s_nop 0
	v_addc_co_u32_e32 v35, vcc, 0, v5, vcc
	global_load_ushort v54, v[34:35], off offset:2048
	v_add_co_u32_e32 v34, vcc, s0, v4
	s_mov_b32 s0, 0x1b000
	s_nop 0
	v_addc_co_u32_e32 v35, vcc, 0, v5, vcc
	global_load_ushort v55, v[34:35], off offset:1024
	v_add_co_u32_e32 v34, vcc, s0, v4
	s_mov_b32 s0, 0x1c000
	s_nop 0
	v_addc_co_u32_e32 v35, vcc, 0, v5, vcc
	global_load_ushort v56, v[34:35], off
	v_add_co_u32_e32 v34, vcc, s0, v4
	s_mov_b32 s0, 0x17000
	s_nop 0
	v_addc_co_u32_e32 v35, vcc, 0, v5, vcc
	global_load_ushort v57, v[34:35], off offset:3072
	v_add_co_u32_e32 v34, vcc, s0, v4
	s_mov_b32 s0, 0x19000
	s_nop 0
	v_addc_co_u32_e32 v35, vcc, 0, v5, vcc
	global_load_ushort v58, v[34:35], off offset:2048
	v_add_co_u32_e32 v34, vcc, s0, v4
	s_mov_b32 s0, 0x14000
	s_nop 0
	v_addc_co_u32_e32 v35, vcc, 0, v5, vcc
	global_load_ushort v59, v[34:35], off offset:1024
	v_add_co_u32_e32 v34, vcc, s0, v4
	s_mov_b32 s0, 0x15000
	s_nop 0
	v_addc_co_u32_e32 v35, vcc, 0, v5, vcc
	global_load_ushort v62, v[34:35], off
	v_add_co_u32_e32 v34, vcc, s0, v4
	s_mov_b32 s0, 0x10000
	s_nop 0
	v_addc_co_u32_e32 v35, vcc, 0, v5, vcc
	global_load_ushort v70, v[34:35], off offset:3072
	v_add_co_u32_e32 v34, vcc, s0, v4
	s_mov_b32 s0, 0x12000
	s_nop 0
	v_addc_co_u32_e32 v35, vcc, 0, v5, vcc
	global_load_ushort v81, v[34:35], off offset:2048
	v_add_co_u32_e32 v34, vcc, s0, v4
	s_mov_b32 s0, 0xd000
	s_nop 0
	v_addc_co_u32_e32 v35, vcc, 0, v5, vcc
	global_load_ushort v107, v[34:35], off offset:1024
	v_add_co_u32_e32 v34, vcc, s0, v4
	s_mov_b32 s0, 0xe000
	s_nop 0
	v_addc_co_u32_e32 v35, vcc, 0, v5, vcc
	global_load_ushort v212, v[34:35], off
	v_add_co_u32_e32 v34, vcc, s0, v4
	s_mov_b32 s0, 0x9000
	s_nop 0
	v_addc_co_u32_e32 v35, vcc, 0, v5, vcc
	global_load_ushort v213, v[34:35], off offset:3072
	v_add_co_u32_e32 v34, vcc, s0, v4
	s_mov_b32 s0, 0xb000
	s_nop 0
	v_addc_co_u32_e32 v35, vcc, 0, v5, vcc
	global_load_ushort v214, v[34:35], off offset:2048
	v_add_co_u32_e32 v34, vcc, s0, v4
	s_movk_i32 s0, 0x6000
	s_nop 0
	v_addc_co_u32_e32 v35, vcc, 0, v5, vcc
	global_load_ushort v215, v[34:35], off offset:1024
	v_add_co_u32_e32 v34, vcc, s0, v4
	s_movk_i32 s0, 0x7000
	s_nop 0
	v_addc_co_u32_e32 v35, vcc, 0, v5, vcc
	global_load_ushort v216, v[34:35], off
	v_add_co_u32_e32 v34, vcc, s0, v4
	s_movk_i32 s0, 0x2000
	s_nop 0
	v_addc_co_u32_e32 v35, vcc, 0, v5, vcc
	global_load_ushort v217, v[34:35], off offset:3072
	v_add_co_u32_e32 v34, vcc, s0, v4
	s_movk_i32 s0, 0x4000
	s_nop 0
	v_addc_co_u32_e32 v35, vcc, 0, v5, vcc
	v_add_co_u32_e32 v4, vcc, s0, v4
	global_load_ushort v218, v[34:35], off offset:2048
	s_nop 0
	v_addc_co_u32_e32 v5, vcc, 0, v5, vcc
	global_load_ushort v219, v[4:5], off offset:1024
	v_mov_b32_e32 v60, v3
	v_pk_mul_f32 v[64:65], v[108:109], v[60:61] op_sel_hi:[0,1]
	s_waitcnt vmcnt(11)
	v_lshlrev_b32_e32 v144, 16, v62
	s_waitcnt vmcnt(1)
	v_lshlrev_b32_e32 v218, 16, v218
	v_pk_fma_f32 v[2:3], v[106:107], v[2:3], v[64:65] op_sel_hi:[0,1,1]
	v_mov_b32_e32 v62, v61
	v_pk_fma_f32 v[2:3], v[110:111], v[62:63], v[2:3] op_sel_hi:[0,1,1]
	v_mov_b32_e32 v60, v63
	v_mov_b32_e32 v61, v218
	v_pk_fma_f32 v[2:3], v[112:113], v[60:61], v[2:3] op_sel_hi:[0,1,1]
	v_mul_f32_e32 v64, 0xbfb8aa3b, v2
	v_mul_f32_e32 v65, 0xbfb8aa3b, v3
	v_exp_f32_e32 v64, v64
	v_exp_f32_e32 v65, v65
	v_pk_mul_f32 v[60:61], v[108:109], v[60:61] op_sel_hi:[0,1]
	v_lshlrev_b32_e32 v217, 16, v217
	v_add_f32_e32 v64, 1.0, v64
	v_add_f32_e32 v65, 1.0, v65
	v_rcp_f32_e32 v64, v64
	v_rcp_f32_e32 v65, v65
	v_lshlrev_b32_e32 v216, 16, v216
	s_waitcnt vmcnt(0)
	v_lshlrev_b32_e32 v219, 16, v219
	v_pk_fma_f32 v[60:61], v[106:107], v[62:63], v[60:61] op_sel_hi:[0,1,1]
	v_pk_mul_f32 v[2:3], v[2:3], v[64:65]
	v_pk_mov_b32 v[64:65], v[218:219], v[216:217] op_sel:[1,0]
	v_pk_fma_f32 v[60:61], v[110:111], v[218:219], v[60:61] op_sel_hi:[0,1,1]
	v_pk_fma_f32 v[60:61], v[112:113], v[64:65], v[60:61] op_sel_hi:[0,1,1]
	v_mul_f32_e32 v62, 0xbfb8aa3b, v60
	v_mul_f32_e32 v63, 0xbfb8aa3b, v61
	v_exp_f32_e32 v62, v62
	v_exp_f32_e32 v63, v63
	v_lshlrev_b32_e32 v121, 16, v8
	v_lshlrev_b32_e32 v120, 16, v6
	v_add_f32_e32 v62, 1.0, v62
	v_add_f32_e32 v63, 1.0, v63
	v_rcp_f32_e32 v62, v62
	v_rcp_f32_e32 v63, v63
	v_lshlrev_b32_e32 v122, 16, v9
	v_lshlrev_b32_e32 v123, 16, v10
	v_lshlrev_b32_e32 v125, 16, v11
	v_lshlrev_b32_e32 v119, 16, v13
	v_lshlrev_b32_e32 v118, 16, v12
	ds_read_b128 v[8:11], v71 offset:51696
	v_lshlrev_b32_e32 v117, 16, v15
	v_lshlrev_b32_e32 v116, 16, v14
	ds_read_b128 v[12:15], v71 offset:51680
	v_lshlrev_b32_e32 v115, 16, v17
	v_lshlrev_b32_e32 v114, 16, v16
	v_lshlrev_b32_e32 v99, 16, v19
	v_lshlrev_b32_e32 v98, 16, v18
	ds_read_b128 v[16:19], v71 offset:51664
	v_lshlrev_b32_e32 v103, 16, v21
	v_lshlrev_b32_e32 v102, 16, v20
	v_lshlrev_b32_e32 v105, 16, v23
	v_lshlrev_b32_e32 v104, 16, v22
	ds_read_b128 v[20:23], v71 offset:51648
	v_lshlrev_b32_e32 v101, 16, v25
	v_lshlrev_b32_e32 v100, 16, v24
	v_lshlrev_b32_e32 v97, 16, v27
	v_lshlrev_b32_e32 v96, 16, v26
	ds_read_b128 v[24:27], v71 offset:51632
	v_lshlrev_b32_e32 v95, 16, v29
	v_lshlrev_b32_e32 v94, 16, v28
	v_lshlrev_b32_e32 v93, 16, v31
	v_lshlrev_b32_e32 v92, 16, v30
	ds_read_b128 v[28:31], v71 offset:51616
	v_lshlrev_b32_e32 v91, 16, v33
	v_lshlrev_b32_e32 v90, 16, v32
	v_lshlrev_b32_e32 v89, 16, v37
	v_lshlrev_b32_e32 v88, 16, v36
	ds_read_b128 v[32:35], v71 offset:51600
	v_lshlrev_b32_e32 v87, 16, v39
	v_lshlrev_b32_e32 v86, 16, v38
	v_lshlrev_b32_e32 v129, 16, v41
	v_lshlrev_b32_e32 v128, 16, v40
	ds_read_b128 v[36:39], v71 offset:51584
	v_lshlrev_b32_e32 v131, 16, v43
	v_lshlrev_b32_e32 v130, 16, v42
	v_lshlrev_b32_e32 v133, 16, v45
	v_lshlrev_b32_e32 v132, 16, v44
	ds_read_b128 v[4:7], v71 offset:51568
	ds_read_b128 v[40:43], v71 offset:51552
	v_lshlrev_b32_e32 v135, 16, v47
	v_lshlrev_b32_e32 v134, 16, v46
	v_lshlrev_b32_e32 v137, 16, v49
	v_lshlrev_b32_e32 v136, 16, v48
	v_lshlrev_b32_e32 v139, 16, v51
	v_lshlrev_b32_e32 v138, 16, v50
	v_lshlrev_b32_e32 v141, 16, v53
	v_lshlrev_b32_e32 v140, 16, v52
	ds_read_b128 v[44:47], v71 offset:51536
	ds_read_b128 v[48:51], v71 offset:51520
	v_lshlrev_b32_e32 v85, 16, v55
	v_lshlrev_b32_e32 v84, 16, v54
	v_lshlrev_b32_e32 v143, 16, v57
	v_lshlrev_b32_e32 v142, 16, v56
	v_lshlrev_b32_e32 v83, 16, v59
	v_lshlrev_b32_e32 v82, 16, v58
	ds_read_b128 v[204:207], v71 offset:51456
	ds_read_b128 v[208:211], v71 offset:51472
	ds_read_b128 v[56:59], v71 offset:51488
	ds_read_b128 v[52:55], v71 offset:51504
	v_pk_mul_f32 v[60:61], v[60:61], v[62:63]
	v_pk_mul_f32 v[62:63], v[108:109], v[64:65] op_sel_hi:[0,1]
	v_lshlrev_b32_e32 v215, 16, v215
	v_lshlrev_b32_e32 v214, 16, v214
	v_pk_fma_f32 v[62:63], v[106:107], v[218:219], v[62:63] op_sel_hi:[0,1,1]
	s_waitcnt lgkmcnt(3)
	v_pk_mul_f32 v[2:3], v[2:3], v[204:205]
	v_pk_mov_b32 v[204:205], v[216:217], v[214:215] op_sel:[1,0]
	v_pk_fma_f32 v[62:63], v[110:111], v[216:217], v[62:63] op_sel_hi:[0,1,1]
	v_pk_fma_f32 v[62:63], v[112:113], v[204:205], v[62:63] op_sel_hi:[0,1,1]
	v_mul_f32_e32 v64, 0xbfb8aa3b, v62
	v_mul_f32_e32 v65, 0xbfb8aa3b, v63
	v_exp_f32_e32 v64, v64
	v_exp_f32_e32 v65, v65
	v_lshlrev_b32_e32 v213, 16, v213
	v_lshlrev_b32_e32 v212, 16, v212
	v_add_f32_e32 v64, 1.0, v64
	v_add_f32_e32 v65, 1.0, v65
	v_rcp_f32_e32 v64, v64
	v_rcp_f32_e32 v65, v65
	v_pk_mul_f32 v[60:61], v[60:61], v[206:207]
	v_pk_mov_b32 v[206:207], v[214:215], v[212:213] op_sel:[1,0]
	v_lshlrev_b32_e32 v145, 16, v70
	v_pk_mul_f32 v[62:63], v[62:63], v[64:65]
	v_pk_mul_f32 v[64:65], v[108:109], v[204:205] op_sel_hi:[0,1]
	v_pk_fma_f32 v[64:65], v[106:107], v[216:217], v[64:65] op_sel_hi:[0,1,1]
	v_pk_fma_f32 v[64:65], v[110:111], v[214:215], v[64:65] op_sel_hi:[0,1,1]
	v_pk_fma_f32 v[64:65], v[112:113], v[206:207], v[64:65] op_sel_hi:[0,1,1]
	v_mul_f32_e32 v70, 0xbfb8aa3b, v64
	v_exp_f32_e32 v70, v70
	v_pk_mul_f32 v[206:207], v[108:109], v[206:207] op_sel_hi:[0,1]
	v_lshlrev_b32_e32 v147, 16, v107
	v_lshlrev_b32_e32 v146, 16, v81
	v_add_f32_e32 v70, 1.0, v70
	v_rcp_f32_e32 v204, v70
	v_mul_f32_e32 v70, 0xbfb8aa3b, v65
	v_exp_f32_e32 v70, v70
	v_pk_fma_f32 v[206:207], v[106:107], v[214:215], v[206:207] op_sel_hi:[0,1,1]
	v_pk_fma_f32 v[206:207], v[110:111], v[212:213], v[206:207] op_sel_hi:[0,1,1]
	s_waitcnt lgkmcnt(2)
	v_pk_mul_f32 v[62:63], v[62:63], v[208:209]
	v_add_f32_e32 v70, 1.0, v70
	v_rcp_f32_e32 v205, v70
	v_mov_b32_e32 v126, v121
	v_mov_b32_e32 v127, v122
	v_mov_b32_e32 v124, v123
	v_pk_mul_f32 v[64:65], v[64:65], v[204:205]
	v_pk_mov_b32 v[204:205], v[212:213], v[146:147] op_sel:[1,0]
	v_pk_mul_f32 v[64:65], v[64:65], v[210:211]
	v_pk_fma_f32 v[206:207], v[112:113], v[204:205], v[206:207] op_sel_hi:[0,1,1]
	v_mul_f32_e32 v70, 0xbfb8aa3b, v206
	v_exp_f32_e32 v70, v70
	v_pk_mul_f32 v[204:205], v[108:109], v[204:205] op_sel_hi:[0,1]
	v_pk_fma_f32 v[204:205], v[106:107], v[212:213], v[204:205] op_sel_hi:[0,1,1]
	v_pk_fma_f32 v[204:205], v[110:111], v[146:147], v[204:205] op_sel_hi:[0,1,1]
	v_add_f32_e32 v70, 1.0, v70
	v_rcp_f32_e32 v208, v70
	v_mul_f32_e32 v70, 0xbfb8aa3b, v207
	v_exp_f32_e32 v70, v70
	s_nop 0
	v_add_f32_e32 v70, 1.0, v70
	v_rcp_f32_e32 v209, v70
	s_nop 0
	v_pk_mul_f32 v[206:207], v[206:207], v[208:209]
	s_waitcnt lgkmcnt(1)
	v_pk_mul_f32 v[56:57], v[206:207], v[56:57]
	v_pk_mov_b32 v[206:207], v[146:147], v[144:145] op_sel:[1,0]
	s_nop 0
	v_pk_fma_f32 v[204:205], v[112:113], v[206:207], v[204:205] op_sel_hi:[0,1,1]
	v_mul_f32_e32 v70, 0xbfb8aa3b, v204
	v_exp_f32_e32 v70, v70
	v_pk_mul_f32 v[206:207], v[108:109], v[206:207] op_sel_hi:[0,1]
	v_pk_fma_f32 v[146:147], v[106:107], v[146:147], v[206:207] op_sel_hi:[0,1,1]
	v_pk_fma_f32 v[146:147], v[110:111], v[144:145], v[146:147] op_sel_hi:[0,1,1]
	v_add_f32_e32 v70, 1.0, v70
	v_rcp_f32_e32 v208, v70
	v_mul_f32_e32 v70, 0xbfb8aa3b, v205
	v_exp_f32_e32 v70, v70
	s_nop 0
	v_add_f32_e32 v70, 1.0, v70
	v_rcp_f32_e32 v209, v70
	s_nop 0
	v_pk_mul_f32 v[204:205], v[204:205], v[208:209]
	s_nop 0
	v_pk_mul_f32 v[58:59], v[204:205], v[58:59]
	v_pk_mov_b32 v[204:205], v[144:145], v[82:83] op_sel:[1,0]
	s_nop 0
	v_pk_fma_f32 v[146:147], v[112:113], v[204:205], v[146:147] op_sel_hi:[0,1,1]
	v_mul_f32_e32 v70, 0xbfb8aa3b, v146
	v_exp_f32_e32 v70, v70
	v_pk_mul_f32 v[204:205], v[108:109], v[204:205] op_sel_hi:[0,1]
	v_pk_fma_f32 v[144:145], v[106:107], v[144:145], v[204:205] op_sel_hi:[0,1,1]
	v_pk_fma_f32 v[144:145], v[110:111], v[82:83], v[144:145] op_sel_hi:[0,1,1]
	v_add_f32_e32 v70, 1.0, v70
	v_rcp_f32_e32 v206, v70
	v_mul_f32_e32 v70, 0xbfb8aa3b, v147
	v_exp_f32_e32 v70, v70
	s_nop 0
	v_add_f32_e32 v70, 1.0, v70
	v_rcp_f32_e32 v207, v70
	s_nop 0
	v_pk_mul_f32 v[146:147], v[146:147], v[206:207]
	s_waitcnt lgkmcnt(0)
	v_pk_mul_f32 v[52:53], v[146:147], v[52:53]
	v_pk_mov_b32 v[146:147], v[82:83], v[142:143] op_sel:[1,0]
	s_nop 0
	v_pk_fma_f32 v[144:145], v[112:113], v[146:147], v[144:145] op_sel_hi:[0,1,1]
	v_mul_f32_e32 v70, 0xbfb8aa3b, v144
	v_exp_f32_e32 v70, v70
	v_pk_mul_f32 v[146:147], v[108:109], v[146:147] op_sel_hi:[0,1]
	v_pk_fma_f32 v[82:83], v[106:107], v[82:83], v[146:147] op_sel_hi:[0,1,1]
	v_pk_fma_f32 v[82:83], v[110:111], v[142:143], v[82:83] op_sel_hi:[0,1,1]
	v_add_f32_e32 v70, 1.0, v70
	v_rcp_f32_e32 v204, v70
	v_mul_f32_e32 v70, 0xbfb8aa3b, v145
	v_exp_f32_e32 v70, v70
	s_nop 0
	v_add_f32_e32 v70, 1.0, v70
	v_rcp_f32_e32 v205, v70
	s_nop 0
	v_pk_mul_f32 v[144:145], v[144:145], v[204:205]
	s_nop 0
	v_pk_mul_f32 v[54:55], v[144:145], v[54:55]
	v_pk_mov_b32 v[144:145], v[142:143], v[84:85] op_sel:[1,0]
	s_nop 0
	v_pk_fma_f32 v[82:83], v[112:113], v[144:145], v[82:83] op_sel_hi:[0,1,1]
	v_mul_f32_e32 v70, 0xbfb8aa3b, v82
	v_exp_f32_e32 v70, v70
	v_pk_mul_f32 v[144:145], v[108:109], v[144:145] op_sel_hi:[0,1]
	v_pk_fma_f32 v[142:143], v[106:107], v[142:143], v[144:145] op_sel_hi:[0,1,1]
	v_pk_fma_f32 v[142:143], v[110:111], v[84:85], v[142:143] op_sel_hi:[0,1,1]
	v_add_f32_e32 v70, 1.0, v70
	v_rcp_f32_e32 v146, v70
	v_mul_f32_e32 v70, 0xbfb8aa3b, v83
	v_exp_f32_e32 v70, v70
	s_nop 0
	v_add_f32_e32 v70, 1.0, v70
	v_rcp_f32_e32 v147, v70
	s_nop 0
	v_pk_mul_f32 v[82:83], v[82:83], v[146:147]
	s_nop 0
	v_pk_mul_f32 v[82:83], v[82:83], v[48:49]
	v_pk_mov_b32 v[48:49], v[84:85], v[140:141] op_sel:[1,0]
	s_nop 0
	v_pk_fma_f32 v[142:143], v[112:113], v[48:49], v[142:143] op_sel_hi:[0,1,1]
	v_mul_f32_e32 v70, 0xbfb8aa3b, v142
	v_exp_f32_e32 v70, v70
	v_pk_mul_f32 v[48:49], v[108:109], v[48:49] op_sel_hi:[0,1]
	v_pk_fma_f32 v[48:49], v[106:107], v[84:85], v[48:49] op_sel_hi:[0,1,1]
	v_pk_fma_f32 v[48:49], v[110:111], v[140:141], v[48:49] op_sel_hi:[0,1,1]
	v_add_f32_e32 v70, 1.0, v70
	v_rcp_f32_e32 v144, v70
	v_mul_f32_e32 v70, 0xbfb8aa3b, v143
	v_exp_f32_e32 v70, v70
	s_nop 0
	v_add_f32_e32 v70, 1.0, v70
	v_rcp_f32_e32 v145, v70
	s_nop 0
	v_pk_mul_f32 v[142:143], v[142:143], v[144:145]
	s_nop 0
	v_pk_mul_f32 v[50:51], v[142:143], v[50:51]
	v_pk_mov_b32 v[142:143], v[140:141], v[138:139] op_sel:[1,0]
	s_nop 0
	v_pk_fma_f32 v[48:49], v[112:113], v[142:143], v[48:49] op_sel_hi:[0,1,1]
	v_mul_f32_e32 v70, 0xbfb8aa3b, v48
	v_exp_f32_e32 v70, v70
	s_nop 0
	v_add_f32_e32 v70, 1.0, v70
	v_rcp_f32_e32 v84, v70
	v_mul_f32_e32 v70, 0xbfb8aa3b, v49
	v_exp_f32_e32 v70, v70
	s_nop 0
	v_add_f32_e32 v70, 1.0, v70
	v_rcp_f32_e32 v85, v70
	s_nop 0
	v_pk_mul_f32 v[48:49], v[48:49], v[84:85]
	s_nop 0
	v_pk_mul_f32 v[84:85], v[48:49], v[44:45]
	v_pk_mul_f32 v[48:49], v[108:109], v[142:143] op_sel_hi:[0,1]
	v_pk_fma_f32 v[48:49], v[106:107], v[140:141], v[48:49] op_sel_hi:[0,1,1]
	v_pk_mov_b32 v[44:45], v[138:139], v[136:137] op_sel:[1,0]
	v_pk_fma_f32 v[48:49], v[110:111], v[138:139], v[48:49] op_sel_hi:[0,1,1]
	v_pk_fma_f32 v[48:49], v[112:113], v[44:45], v[48:49] op_sel_hi:[0,1,1]
	v_mul_f32_e32 v70, 0xbfb8aa3b, v48
	v_exp_f32_e32 v70, v70
	v_pk_mul_f32 v[44:45], v[108:109], v[44:45] op_sel_hi:[0,1]
	v_pk_fma_f32 v[44:45], v[106:107], v[138:139], v[44:45] op_sel_hi:[0,1,1]
	v_pk_fma_f32 v[44:45], v[110:111], v[136:137], v[44:45] op_sel_hi:[0,1,1]
	v_add_f32_e32 v70, 1.0, v70
	v_rcp_f32_e32 v140, v70
	v_mul_f32_e32 v70, 0xbfb8aa3b, v49
	v_exp_f32_e32 v70, v70
	s_nop 0
	v_add_f32_e32 v70, 1.0, v70
	v_rcp_f32_e32 v141, v70
	s_nop 0
	v_pk_mul_f32 v[48:49], v[48:49], v[140:141]
	v_pk_mov_b32 v[140:141], v[136:137], v[134:135] op_sel:[1,0]
	v_pk_mul_f32 v[48:49], v[48:49], v[46:47]
	v_pk_fma_f32 v[44:45], v[112:113], v[140:141], v[44:45] op_sel_hi:[0,1,1]
	v_mul_f32_e32 v46, 0xbfb8aa3b, v44
	v_mul_f32_e32 v47, 0xbfb8aa3b, v45
	v_exp_f32_e32 v46, v46
	v_exp_f32_e32 v47, v47
	v_add_f32_e32 v46, 1.0, v46
	v_add_f32_e32 v47, 1.0, v47
	v_rcp_f32_e32 v46, v46
	v_rcp_f32_e32 v47, v47
	s_nop 0
	v_pk_mul_f32 v[44:45], v[44:45], v[46:47]
	s_nop 0
	v_pk_mul_f32 v[46:47], v[44:45], v[40:41]
	v_pk_mul_f32 v[44:45], v[108:109], v[140:141] op_sel_hi:[0,1]
	v_pk_fma_f32 v[44:45], v[106:107], v[136:137], v[44:45] op_sel_hi:[0,1,1]
	v_pk_mov_b32 v[40:41], v[134:135], v[132:133] op_sel:[1,0]
	v_pk_fma_f32 v[44:45], v[110:111], v[134:135], v[44:45] op_sel_hi:[0,1,1]
	v_pk_fma_f32 v[44:45], v[112:113], v[40:41], v[44:45] op_sel_hi:[0,1,1]
	v_mul_f32_e32 v70, 0xbfb8aa3b, v44
	v_exp_f32_e32 v70, v70
	v_pk_mul_f32 v[40:41], v[108:109], v[40:41] op_sel_hi:[0,1]
	v_pk_fma_f32 v[40:41], v[106:107], v[134:135], v[40:41] op_sel_hi:[0,1,1]
	v_pk_fma_f32 v[40:41], v[110:111], v[132:133], v[40:41] op_sel_hi:[0,1,1]
	v_add_f32_e32 v70, 1.0, v70
	v_rcp_f32_e32 v136, v70
	v_mul_f32_e32 v70, 0xbfb8aa3b, v45
	v_exp_f32_e32 v70, v70
	s_nop 0
	v_add_f32_e32 v70, 1.0, v70
	v_rcp_f32_e32 v137, v70
	s_nop 0
	v_pk_mul_f32 v[44:45], v[44:45], v[136:137]
	v_pk_mov_b32 v[136:137], v[132:133], v[130:131] op_sel:[1,0]
	v_pk_mul_f32 v[44:45], v[44:45], v[42:43]
	v_pk_fma_f32 v[40:41], v[112:113], v[136:137], v[40:41] op_sel_hi:[0,1,1]
	v_mul_f32_e32 v42, 0xbfb8aa3b, v40
	v_mul_f32_e32 v43, 0xbfb8aa3b, v41
	v_exp_f32_e32 v42, v42
	v_exp_f32_e32 v43, v43
	v_add_f32_e32 v42, 1.0, v42
	v_add_f32_e32 v43, 1.0, v43
	v_rcp_f32_e32 v42, v42
	v_rcp_f32_e32 v43, v43
	s_nop 0
	v_pk_mul_f32 v[40:41], v[40:41], v[42:43]
	s_nop 0
	v_pk_mul_f32 v[42:43], v[40:41], v[4:5]
	v_pk_mul_f32 v[40:41], v[108:109], v[136:137] op_sel_hi:[0,1]
	v_pk_fma_f32 v[40:41], v[106:107], v[132:133], v[40:41] op_sel_hi:[0,1,1]
	v_pk_mov_b32 v[4:5], v[130:131], v[128:129] op_sel:[1,0]
	v_pk_fma_f32 v[40:41], v[110:111], v[130:131], v[40:41] op_sel_hi:[0,1,1]
	v_pk_fma_f32 v[40:41], v[112:113], v[4:5], v[40:41] op_sel_hi:[0,1,1]
	v_mul_f32_e32 v70, 0xbfb8aa3b, v40
	v_exp_f32_e32 v70, v70
	v_pk_mul_f32 v[4:5], v[108:109], v[4:5] op_sel_hi:[0,1]
	v_pk_fma_f32 v[4:5], v[106:107], v[130:131], v[4:5] op_sel_hi:[0,1,1]
	v_pk_fma_f32 v[4:5], v[110:111], v[128:129], v[4:5] op_sel_hi:[0,1,1]
	v_add_f32_e32 v70, 1.0, v70
	v_rcp_f32_e32 v132, v70
	v_mul_f32_e32 v70, 0xbfb8aa3b, v41
	v_exp_f32_e32 v70, v70
	s_nop 0
	v_add_f32_e32 v70, 1.0, v70
	v_rcp_f32_e32 v133, v70
	s_nop 0
	v_pk_mul_f32 v[40:41], v[40:41], v[132:133]
	v_pk_mov_b32 v[132:133], v[128:129], v[86:87] op_sel:[1,0]
	v_pk_mul_f32 v[40:41], v[40:41], v[6:7]
	v_pk_fma_f32 v[4:5], v[112:113], v[132:133], v[4:5] op_sel_hi:[0,1,1]
	v_mul_f32_e32 v6, 0xbfb8aa3b, v4
	v_mul_f32_e32 v7, 0xbfb8aa3b, v5
	v_exp_f32_e32 v6, v6
	v_exp_f32_e32 v7, v7
	v_add_f32_e32 v6, 1.0, v6
	v_add_f32_e32 v7, 1.0, v7
	v_rcp_f32_e32 v6, v6
	v_rcp_f32_e32 v7, v7
	s_nop 0
	v_pk_mul_f32 v[4:5], v[4:5], v[6:7]
	s_nop 0
	v_pk_mul_f32 v[6:7], v[4:5], v[36:37]
	v_pk_mul_f32 v[36:37], v[108:109], v[132:133] op_sel_hi:[0,1]
	v_pk_fma_f32 v[36:37], v[106:107], v[128:129], v[36:37] op_sel_hi:[0,1,1]
	v_pk_mov_b32 v[4:5], v[86:87], v[88:89] op_sel:[1,0]
	v_pk_fma_f32 v[36:37], v[110:111], v[86:87], v[36:37] op_sel_hi:[0,1,1]
	v_pk_fma_f32 v[36:37], v[112:113], v[4:5], v[36:37] op_sel_hi:[0,1,1]
	v_mul_f32_e32 v70, 0xbfb8aa3b, v36
	v_exp_f32_e32 v70, v70
	v_pk_mul_f32 v[4:5], v[108:109], v[4:5] op_sel_hi:[0,1]
	v_pk_fma_f32 v[4:5], v[106:107], v[86:87], v[4:5] op_sel_hi:[0,1,1]
	v_pk_fma_f32 v[4:5], v[110:111], v[88:89], v[4:5] op_sel_hi:[0,1,1]
	v_add_f32_e32 v70, 1.0, v70
	v_rcp_f32_e32 v128, v70
	v_mul_f32_e32 v70, 0xbfb8aa3b, v37
	v_exp_f32_e32 v70, v70
	s_nop 0
	v_add_f32_e32 v70, 1.0, v70
	v_rcp_f32_e32 v129, v70
	s_nop 0
	v_pk_mul_f32 v[36:37], v[36:37], v[128:129]
	s_nop 0
	v_pk_mul_f32 v[38:39], v[36:37], v[38:39]
	v_pk_mov_b32 v[36:37], v[88:89], v[90:91] op_sel:[1,0]
	s_nop 0
	v_pk_fma_f32 v[4:5], v[112:113], v[36:37], v[4:5] op_sel_hi:[0,1,1]
	v_mul_f32_e32 v70, 0xbfb8aa3b, v4
	v_exp_f32_e32 v70, v70
	s_nop 0
	v_add_f32_e32 v70, 1.0, v70
	v_rcp_f32_e32 v86, v70
	v_mul_f32_e32 v70, 0xbfb8aa3b, v5
	v_exp_f32_e32 v70, v70
	s_nop 0
	v_add_f32_e32 v70, 1.0, v70
	v_rcp_f32_e32 v87, v70
	s_nop 0
	v_pk_mul_f32 v[4:5], v[4:5], v[86:87]
	s_nop 0
	v_pk_mul_f32 v[86:87], v[4:5], v[32:33]
	v_pk_mul_f32 v[32:33], v[108:109], v[36:37] op_sel_hi:[0,1]
	v_pk_fma_f32 v[32:33], v[106:107], v[88:89], v[32:33] op_sel_hi:[0,1,1]
	v_pk_mov_b32 v[4:5], v[90:91], v[92:93] op_sel:[1,0]
	v_pk_fma_f32 v[32:33], v[110:111], v[90:91], v[32:33] op_sel_hi:[0,1,1]
	v_pk_fma_f32 v[32:33], v[112:113], v[4:5], v[32:33] op_sel_hi:[0,1,1]
	v_mul_f32_e32 v36, 0xbfb8aa3b, v32
	v_mul_f32_e32 v37, 0xbfb8aa3b, v33
	v_exp_f32_e32 v36, v36
	v_exp_f32_e32 v37, v37
	v_pk_mul_f32 v[4:5], v[108:109], v[4:5] op_sel_hi:[0,1]
	v_pk_fma_f32 v[4:5], v[106:107], v[90:91], v[4:5] op_sel_hi:[0,1,1]
	v_add_f32_e32 v36, 1.0, v36
	v_add_f32_e32 v37, 1.0, v37
	v_rcp_f32_e32 v36, v36
	v_rcp_f32_e32 v37, v37
	v_pk_fma_f32 v[4:5], v[110:111], v[92:93], v[4:5] op_sel_hi:[0,1,1]
	v_pk_mul_f32 v[32:33], v[32:33], v[36:37]
	s_nop 0
	v_pk_mul_f32 v[88:89], v[32:33], v[34:35]
	v_pk_mov_b32 v[32:33], v[92:93], v[94:95] op_sel:[1,0]
	s_nop 0
	v_pk_fma_f32 v[4:5], v[112:113], v[32:33], v[4:5] op_sel_hi:[0,1,1]
	v_mul_f32_e32 v34, 0xbfb8aa3b, v4
	v_mul_f32_e32 v35, 0xbfb8aa3b, v5
	v_exp_f32_e32 v34, v34
	v_exp_f32_e32 v35, v35
	v_add_f32_e32 v34, 1.0, v34
	v_add_f32_e32 v35, 1.0, v35
	v_rcp_f32_e32 v34, v34
	v_rcp_f32_e32 v35, v35
	s_nop 0
	v_pk_mul_f32 v[4:5], v[4:5], v[34:35]
	s_nop 0
	v_pk_mul_f32 v[90:91], v[4:5], v[28:29]
	v_pk_mul_f32 v[28:29], v[108:109], v[32:33] op_sel_hi:[0,1]
	v_pk_fma_f32 v[28:29], v[106:107], v[92:93], v[28:29] op_sel_hi:[0,1,1]
	v_pk_mov_b32 v[4:5], v[94:95], v[96:97] op_sel:[1,0]
	v_pk_fma_f32 v[28:29], v[110:111], v[94:95], v[28:29] op_sel_hi:[0,1,1]
	v_pk_fma_f32 v[28:29], v[112:113], v[4:5], v[28:29] op_sel_hi:[0,1,1]
	v_mul_f32_e32 v32, 0xbfb8aa3b, v28
	v_mul_f32_e32 v33, 0xbfb8aa3b, v29
	v_exp_f32_e32 v32, v32
	v_exp_f32_e32 v33, v33
	v_pk_mul_f32 v[4:5], v[108:109], v[4:5] op_sel_hi:[0,1]
	v_pk_fma_f32 v[4:5], v[106:107], v[94:95], v[4:5] op_sel_hi:[0,1,1]
	v_add_f32_e32 v32, 1.0, v32
	v_add_f32_e32 v33, 1.0, v33
	v_rcp_f32_e32 v32, v32
	v_rcp_f32_e32 v33, v33
	v_pk_fma_f32 v[4:5], v[110:111], v[96:97], v[4:5] op_sel_hi:[0,1,1]
	v_pk_mul_f32 v[28:29], v[28:29], v[32:33]
	s_nop 0
	v_pk_mul_f32 v[92:93], v[28:29], v[30:31]
	v_pk_mov_b32 v[28:29], v[96:97], v[100:101] op_sel:[1,0]
	s_nop 0
	v_pk_fma_f32 v[4:5], v[112:113], v[28:29], v[4:5] op_sel_hi:[0,1,1]
	v_mul_f32_e32 v30, 0xbfb8aa3b, v4
	v_mul_f32_e32 v31, 0xbfb8aa3b, v5
	v_exp_f32_e32 v30, v30
	v_exp_f32_e32 v31, v31
	v_add_f32_e32 v30, 1.0, v30
	v_add_f32_e32 v31, 1.0, v31
	v_rcp_f32_e32 v30, v30
	v_rcp_f32_e32 v31, v31
	s_nop 0
	v_pk_mul_f32 v[4:5], v[4:5], v[30:31]
	s_nop 0
	v_pk_mul_f32 v[94:95], v[4:5], v[24:25]
	v_pk_mul_f32 v[24:25], v[108:109], v[28:29] op_sel_hi:[0,1]
	v_pk_fma_f32 v[24:25], v[106:107], v[96:97], v[24:25] op_sel_hi:[0,1,1]
	v_pk_mov_b32 v[4:5], v[100:101], v[104:105] op_sel:[1,0]
	v_pk_fma_f32 v[24:25], v[110:111], v[100:101], v[24:25] op_sel_hi:[0,1,1]
	v_pk_fma_f32 v[24:25], v[112:113], v[4:5], v[24:25] op_sel_hi:[0,1,1]
	v_mul_f32_e32 v28, 0xbfb8aa3b, v24
	v_mul_f32_e32 v29, 0xbfb8aa3b, v25
	v_exp_f32_e32 v28, v28
	v_exp_f32_e32 v29, v29
	v_pk_mul_f32 v[4:5], v[108:109], v[4:5] op_sel_hi:[0,1]
	v_pk_fma_f32 v[4:5], v[106:107], v[100:101], v[4:5] op_sel_hi:[0,1,1]
	v_add_f32_e32 v28, 1.0, v28
	v_add_f32_e32 v29, 1.0, v29
	v_rcp_f32_e32 v28, v28
	v_rcp_f32_e32 v29, v29
	v_pk_fma_f32 v[4:5], v[110:111], v[104:105], v[4:5] op_sel_hi:[0,1,1]
	v_pk_mul_f32 v[24:25], v[24:25], v[28:29]
	s_nop 0
	v_pk_mul_f32 v[96:97], v[24:25], v[26:27]
	v_pk_mov_b32 v[24:25], v[104:105], v[102:103] op_sel:[1,0]
	s_nop 0
	v_pk_fma_f32 v[4:5], v[112:113], v[24:25], v[4:5] op_sel_hi:[0,1,1]
	v_mul_f32_e32 v26, 0xbfb8aa3b, v4
	v_mul_f32_e32 v27, 0xbfb8aa3b, v5
	v_exp_f32_e32 v26, v26
	v_exp_f32_e32 v27, v27
	v_add_f32_e32 v26, 1.0, v26
	v_add_f32_e32 v27, 1.0, v27
	v_rcp_f32_e32 v26, v26
	v_rcp_f32_e32 v27, v27
	s_nop 0
	v_pk_mul_f32 v[4:5], v[4:5], v[26:27]
	s_nop 0
	v_pk_mul_f32 v[100:101], v[4:5], v[20:21]
	v_pk_mul_f32 v[20:21], v[108:109], v[24:25] op_sel_hi:[0,1]
	v_pk_fma_f32 v[20:21], v[106:107], v[104:105], v[20:21] op_sel_hi:[0,1,1]
	v_pk_mov_b32 v[4:5], v[102:103], v[98:99] op_sel:[1,0]
	v_pk_fma_f32 v[20:21], v[110:111], v[102:103], v[20:21] op_sel_hi:[0,1,1]
	v_pk_fma_f32 v[20:21], v[112:113], v[4:5], v[20:21] op_sel_hi:[0,1,1]
	v_mul_f32_e32 v24, 0xbfb8aa3b, v20
	v_mul_f32_e32 v25, 0xbfb8aa3b, v21
	v_exp_f32_e32 v24, v24
	v_exp_f32_e32 v25, v25
	v_pk_mul_f32 v[4:5], v[108:109], v[4:5] op_sel_hi:[0,1]
	v_pk_fma_f32 v[4:5], v[106:107], v[102:103], v[4:5] op_sel_hi:[0,1,1]
	v_add_f32_e32 v24, 1.0, v24
	v_add_f32_e32 v25, 1.0, v25
	v_rcp_f32_e32 v24, v24
	v_rcp_f32_e32 v25, v25
	v_pk_fma_f32 v[4:5], v[110:111], v[98:99], v[4:5] op_sel_hi:[0,1,1]
	v_pk_mul_f32 v[20:21], v[20:21], v[24:25]
	s_nop 0
	v_pk_mul_f32 v[104:105], v[20:21], v[22:23]
	v_pk_mov_b32 v[20:21], v[98:99], v[114:115] op_sel:[1,0]
	s_nop 0
	v_pk_fma_f32 v[4:5], v[112:113], v[20:21], v[4:5] op_sel_hi:[0,1,1]
	v_mul_f32_e32 v22, 0xbfb8aa3b, v4
	v_mul_f32_e32 v23, 0xbfb8aa3b, v5
	v_exp_f32_e32 v22, v22
	v_exp_f32_e32 v23, v23
	v_add_f32_e32 v22, 1.0, v22
	v_add_f32_e32 v23, 1.0, v23
	v_rcp_f32_e32 v22, v22
	v_rcp_f32_e32 v23, v23
	s_nop 0
	v_pk_mul_f32 v[4:5], v[4:5], v[22:23]
	s_nop 0
	v_pk_mul_f32 v[102:103], v[4:5], v[16:17]
	v_pk_mul_f32 v[16:17], v[108:109], v[20:21] op_sel_hi:[0,1]
	v_pk_fma_f32 v[16:17], v[106:107], v[98:99], v[16:17] op_sel_hi:[0,1,1]
	v_pk_mov_b32 v[4:5], v[114:115], v[116:117] op_sel:[1,0]
	v_pk_fma_f32 v[16:17], v[110:111], v[114:115], v[16:17] op_sel_hi:[0,1,1]
	v_pk_fma_f32 v[16:17], v[112:113], v[4:5], v[16:17] op_sel_hi:[0,1,1]
	v_mul_f32_e32 v20, 0xbfb8aa3b, v16
	v_mul_f32_e32 v21, 0xbfb8aa3b, v17
	v_exp_f32_e32 v20, v20
	v_exp_f32_e32 v21, v21
	v_pk_mul_f32 v[4:5], v[108:109], v[4:5] op_sel_hi:[0,1]
	v_pk_fma_f32 v[4:5], v[106:107], v[114:115], v[4:5] op_sel_hi:[0,1,1]
	v_add_f32_e32 v20, 1.0, v20
	v_add_f32_e32 v21, 1.0, v21
	v_rcp_f32_e32 v20, v20
	v_rcp_f32_e32 v21, v21
	v_pk_fma_f32 v[4:5], v[110:111], v[116:117], v[4:5] op_sel_hi:[0,1,1]
	v_pk_mul_f32 v[16:17], v[16:17], v[20:21]
	s_nop 0
	v_pk_mul_f32 v[98:99], v[16:17], v[18:19]
	v_pk_mov_b32 v[16:17], v[116:117], v[118:119] op_sel:[1,0]
	s_nop 0
	v_pk_fma_f32 v[4:5], v[112:113], v[16:17], v[4:5] op_sel_hi:[0,1,1]
	v_mul_f32_e32 v18, 0xbfb8aa3b, v4
	v_mul_f32_e32 v19, 0xbfb8aa3b, v5
	v_exp_f32_e32 v18, v18
	v_exp_f32_e32 v19, v19
	v_add_f32_e32 v18, 1.0, v18
	v_add_f32_e32 v19, 1.0, v19
	v_rcp_f32_e32 v18, v18
	v_rcp_f32_e32 v19, v19
	s_nop 0
	v_pk_mul_f32 v[4:5], v[4:5], v[18:19]
	s_nop 0
	v_pk_mul_f32 v[114:115], v[4:5], v[12:13]
	v_pk_mul_f32 v[12:13], v[108:109], v[16:17] op_sel_hi:[0,1]
	v_pk_fma_f32 v[12:13], v[106:107], v[116:117], v[12:13] op_sel_hi:[0,1,1]
	v_pk_mov_b32 v[4:5], v[118:119], v[120:121] op_sel:[1,0]
	v_pk_fma_f32 v[12:13], v[110:111], v[118:119], v[12:13] op_sel_hi:[0,1,1]
	v_pk_fma_f32 v[12:13], v[112:113], v[4:5], v[12:13] op_sel_hi:[0,1,1]
	v_mul_f32_e32 v16, 0xbfb8aa3b, v12
	v_mul_f32_e32 v17, 0xbfb8aa3b, v13
	v_exp_f32_e32 v16, v16
	v_exp_f32_e32 v17, v17
	v_pk_mul_f32 v[4:5], v[108:109], v[4:5] op_sel_hi:[0,1]
	v_pk_fma_f32 v[4:5], v[106:107], v[118:119], v[4:5] op_sel_hi:[0,1,1]
	v_add_f32_e32 v16, 1.0, v16
	v_add_f32_e32 v17, 1.0, v17
	v_rcp_f32_e32 v16, v16
	v_rcp_f32_e32 v17, v17
	v_pk_fma_f32 v[4:5], v[110:111], v[120:121], v[4:5] op_sel_hi:[0,1,1]
	v_pk_mul_f32 v[12:13], v[12:13], v[16:17]
	s_nop 0
	v_pk_mul_f32 v[116:117], v[12:13], v[14:15]
	v_pk_mov_b32 v[12:13], v[120:121], v[122:123] op_sel:[1,0]
	s_nop 0
	v_pk_fma_f32 v[4:5], v[112:113], v[12:13], v[4:5] op_sel_hi:[0,1,1]
	v_mul_f32_e32 v12, 0xbfb8aa3b, v4
	v_mul_f32_e32 v13, 0xbfb8aa3b, v5
	v_exp_f32_e32 v12, v12
	v_exp_f32_e32 v13, v13
	v_add_f32_e32 v12, 1.0, v12
	v_add_f32_e32 v13, 1.0, v13
	v_rcp_f32_e32 v12, v12
	v_rcp_f32_e32 v13, v13
	s_nop 0
	v_pk_mul_f32 v[4:5], v[4:5], v[12:13]
	s_nop 0
	v_pk_mul_f32 v[118:119], v[4:5], v[8:9]
	v_pk_mul_f32 v[4:5], v[108:109], v[126:127] op_sel_hi:[0,1]
	v_pk_fma_f32 v[4:5], v[106:107], v[120:121], v[4:5] op_sel_hi:[0,1,1]
	v_pk_fma_f32 v[4:5], v[110:111], v[122:123], v[4:5] op_sel_hi:[0,1,1]
	v_pk_fma_f32 v[4:5], v[112:113], v[124:125], v[4:5] op_sel_hi:[0,1,1]
	v_mul_f32_e32 v8, 0xbfb8aa3b, v4
	v_mul_f32_e32 v9, 0xbfb8aa3b, v5
	v_exp_f32_e32 v8, v8
	v_exp_f32_e32 v9, v9
	v_add_f32_e32 v8, 1.0, v8
	v_add_f32_e32 v9, 1.0, v9
	v_rcp_f32_e32 v8, v8
	v_rcp_f32_e32 v9, v9
	s_nop 0
	v_pk_mul_f32 v[4:5], v[4:5], v[8:9]
	s_nop 0
	v_pk_mul_f32 v[106:107], v[4:5], v[10:11]

.LBB0_289:
	s_or_b64 exec, exec, s[0:1]
	s_waitcnt lgkmcnt(0)
	s_barrier
	ds_read2_b64 v[2:5], v162 offset1:4
	v_lshl_add_u64 v[6:7], v[66:67], 4, s[38:39]
	s_cmp_lg_u32 s68, 31
	s_waitcnt lgkmcnt(0)
	global_store_dwordx4 v[6:7], v[2:5], off
	ds_read2_b64 v[2:5], v162 offset0:8 offset1:12
	s_waitcnt lgkmcnt(0)
	global_store_dwordx4 v[6:7], v[2:5], off offset:1024
	ds_read2_b64 v[2:5], v162 offset0:16 offset1:20
	s_waitcnt lgkmcnt(0)
	global_store_dwordx4 v[6:7], v[2:5], off offset:2048
	ds_read2_b64 v[2:5], v162 offset0:24 offset1:28
	s_waitcnt lgkmcnt(0)
	global_store_dwordx4 v[6:7], v[2:5], off offset:3072
	s_cbranch_scc1 .LBB0_185
	s_or_b32 s3, s67, 61
	s_mul_i32 s38, s66, 3
	s_movk_i32 s39, 0x1800
	v_mov_b32_e32 v4, v0
	v_mul_u32_u24_e32 v5, 0xaaab, v4
	v_lshrrev_b32_e32 v5, 24, v5
	v_mul_u32_u24_e32 v6, 0x180, v5
	v_sub_u32_e32 v6, v4, v6
	v_add_u32_e32 v7, s3, v5
	v_mov_b64_e32 v[10:11], s[74:75]
	v_mad_i64_i32 v[10:11], s[54:55], v7, s64, v[10:11]
	v_and_b32_e32 v7, 0x7f, v6
	v_lshlrev_b32_e32 v6, 2, v6
	v_and_b32_e32 v6, 0x600, v6
	v_or3_b32 v6, v7, v6, s26
	v_lshlrev_b32_e32 v14, 1, v6
	v_mov_b32_e32 v15, 0
	v_lshl_add_u64 v[10:11], v[10:11], 0, v[14:15]
	global_load_ushort v8, v[10:11], off offset:3072
	v_add_u32_e32 v5, s38, v5
	v_mov_b64_e32 v[12:13], s[34:35]
	v_mad_i64_i32 v[12:13], s[54:55], v5, s39, v[12:13]
	v_lshlrev_b32_e32 v14, 2, v6
	v_lshl_add_u64 v[12:13], v[12:13], 0, v[14:15]
	v_add_u32_e32 v16, 0x100, v0
	v_mul_u32_u24_e32 v17, 0xaaab, v16
	v_lshrrev_b32_e32 v17, 24, v17
	v_mul_u32_u24_e32 v18, 0x180, v17
	v_sub_u32_e32 v18, v16, v18
	v_add_u32_e32 v19, s3, v17
	v_mov_b64_e32 v[22:23], s[74:75]
	v_mad_i64_i32 v[22:23], s[54:55], v19, s64, v[22:23]
	v_and_b32_e32 v19, 0x7f, v18
	v_lshlrev_b32_e32 v18, 2, v18
	v_and_b32_e32 v18, 0x600, v18
	v_or3_b32 v18, v19, v18, s26
	v_lshlrev_b32_e32 v26, 1, v18
	v_mov_b32_e32 v27, 0
	v_lshl_add_u64 v[22:23], v[22:23], 0, v[26:27]
	global_load_ushort v20, v[22:23], off offset:3072
	v_add_u32_e32 v17, s38, v17
	v_mov_b64_e32 v[24:25], s[34:35]
	v_mad_i64_i32 v[24:25], s[54:55], v17, s39, v[24:25]
	v_lshlrev_b32_e32 v26, 2, v18
	v_lshl_add_u64 v[24:25], v[24:25], 0, v[26:27]
	v_add_u32_e32 v28, 0x200, v0
	v_mul_u32_u24_e32 v29, 0xaaab, v28
	v_lshrrev_b32_e32 v29, 24, v29
	v_mul_u32_u24_e32 v30, 0x180, v29
	v_sub_u32_e32 v30, v28, v30
	v_add_u32_e32 v31, s3, v29
	v_mov_b64_e32 v[34:35], s[74:75]
	v_mad_i64_i32 v[34:35], s[54:55], v31, s64, v[34:35]
	v_and_b32_e32 v31, 0x7f, v30
	v_lshlrev_b32_e32 v30, 2, v30
	v_and_b32_e32 v30, 0x600, v30
	v_or3_b32 v30, v31, v30, s26
	v_lshlrev_b32_e32 v38, 1, v30
	v_mov_b32_e32 v39, 0
	v_lshl_add_u64 v[34:35], v[34:35], 0, v[38:39]
	global_load_ushort v32, v[34:35], off offset:3072
	v_add_u32_e32 v29, s38, v29
	v_mov_b64_e32 v[36:37], s[34:35]
	v_mad_i64_i32 v[36:37], s[54:55], v29, s39, v[36:37]
	v_lshlrev_b32_e32 v38, 2, v30
	v_lshl_add_u64 v[36:37], v[36:37], 0, v[38:39]
	v_add_u32_e32 v40, 0x300, v0
	v_mul_u32_u24_e32 v41, 0xaaab, v40
	v_lshrrev_b32_e32 v41, 24, v41
	v_mul_u32_u24_e32 v42, 0x180, v41
	v_sub_u32_e32 v42, v40, v42
	v_add_u32_e32 v43, s3, v41
	v_mov_b64_e32 v[46:47], s[74:75]
	v_mad_i64_i32 v[46:47], s[54:55], v43, s64, v[46:47]
	v_and_b32_e32 v43, 0x7f, v42
	v_lshlrev_b32_e32 v42, 2, v42
	v_and_b32_e32 v42, 0x600, v42
	v_or3_b32 v42, v43, v42, s26
	v_lshlrev_b32_e32 v50, 1, v42
	v_mov_b32_e32 v51, 0
	v_lshl_add_u64 v[46:47], v[46:47], 0, v[50:51]
	global_load_ushort v44, v[46:47], off offset:3072
	v_add_u32_e32 v41, s38, v41
	v_mov_b64_e32 v[48:49], s[34:35]
	v_mad_i64_i32 v[48:49], s[54:55], v41, s39, v[48:49]
	v_lshlrev_b32_e32 v50, 2, v42
	v_lshl_add_u64 v[48:49], v[48:49], 0, v[50:51]
	s_cmp_lt_u32 s98, 0x800
	s_cbranch_scc0 .Ldqcp_a
	v_add_u32_e32 v52, 0x400, v0
	v_mul_u32_u24_e32 v53, 0xaaab, v52
	v_lshrrev_b32_e32 v53, 24, v53
	v_mul_u32_u24_e32 v54, 0x180, v53
	v_sub_u32_e32 v54, v52, v54
	v_add_u32_e32 v55, s3, v53
	v_mov_b64_e32 v[58:59], s[74:75]
	v_mad_i64_i32 v[58:59], s[54:55], v55, s64, v[58:59]
	v_and_b32_e32 v55, 0x7f, v54
	v_lshlrev_b32_e32 v54, 2, v54
	v_and_b32_e32 v54, 0x600, v54
	v_or3_b32 v54, v55, v54, s26
	v_lshlrev_b32_e32 v62, 1, v54
	v_mov_b32_e32 v63, 0
	v_lshl_add_u64 v[58:59], v[58:59], 0, v[62:63]
	global_load_ushort v56, v[58:59], off offset:3072
	v_add_u32_e32 v53, s38, v53
	v_mov_b64_e32 v[60:61], s[34:35]
	v_mad_i64_i32 v[60:61], s[54:55], v53, s39, v[60:61]
	v_lshlrev_b32_e32 v62, 2, v54
	v_lshl_add_u64 v[60:61], v[60:61], 0, v[62:63]
.Ldqcp_a:
	s_waitcnt vmcnt(0)
	v_lshlrev_b32_e32 v8, 16, v8
	global_store_dword v[12:13], v8, off
	v_lshlrev_b32_e32 v20, 16, v20
	global_store_dword v[24:25], v20, off
	v_lshlrev_b32_e32 v32, 16, v32
	global_store_dword v[36:37], v32, off
	v_lshlrev_b32_e32 v44, 16, v44
	global_store_dword v[48:49], v44, off
	s_cmp_lt_u32 s98, 0x800
	s_cbranch_scc0 .Ldqcp_b
	v_lshlrev_b32_e32 v56, 16, v56
	global_store_dword v[60:61], v56, off
.Ldqcp_b:
	s_branch .LBB0_185
.LBB0_293:
	ds_read_b32 v2, v159 offset:51396
	s_waitcnt lgkmcnt(0)
	v_sub_f32_e32 v2, v54, v2
	v_mul_f32_e32 v2, 0x3fb8aa3b, v2
	v_exp_f32_e32 v2, v2
	s_nop 0
	v_mul_f32_e32 v35, v3, v2
	s_or_b64 exec, exec, s[56:57]
	s_and_saveexec_b64 s[56:57], s[90:91]
	s_cbranch_execz .LBB0_268

.LBB0_562:
	s_or_b64 exec, exec, s[60:61]
	s_waitcnt lgkmcnt(0)
	s_barrier
	ds_read2_b64 v[6:9], v163 offset1:4
	v_lshlrev_b32_e32 v4, 4, v0
	v_readlane_b32 s76, v236, 3
	v_lshl_add_u64 v[2:3], s[56:57], 0, v[4:5]
	s_addk_i32 s62, 0x4005
	s_waitcnt lgkmcnt(0)
	global_store_dwordx4 v4, v[6:9], s[56:57]
	s_mov_b64 s[54:55], 0
	v_readlane_b32 s77, v236, 4
	s_movk_i32 s52, 0x1c00
	v_mov_b32_e32 v50, v0
	v_mul_u32_u24_e32 v52, 0xaaab, v50
	v_lshrrev_b32_e32 v52, 24, v52
	v_mov_b32_e32 v53, 0
	v_mul_u32_u24_e32 v51, 0x180, v52
	v_sub_u32_e32 v51, v50, v51
	v_add_u32_e32 v54, s62, v52
	v_mov_b64_e32 v[56:57], s[76:77]
	v_mad_i64_i32 v[56:57], s[60:61], v54, s52, v[56:57]
	v_and_b32_e32 v54, 0x7f, v51
	v_lshlrev_b32_e32 v51, 2, v51
	v_and_b32_e32 v51, 0x600, v51
	v_or3_b32 v51, v54, v51, s63
	v_lshlrev_b32_e32 v60, 1, v51
	v_mov_b32_e32 v61, 0
	v_lshl_add_u64 v[56:57], v[56:57], 0, v[60:61]
	global_load_ushort v55, v[56:57], off offset:3072
	v_mov_b64_e32 v[58:59], s[0:1]
	v_lshl_add_u64 v[52:53], v[52:53], 0, s[2:3]
	v_mad_u64_u32 v[58:59], s[60:61], v52, s74, v[58:59]
	v_mad_i32_i24 v59, v53, s74, v59
	v_lshlrev_b32_e32 v60, 2, v51
	v_lshl_add_u64 v[58:59], v[58:59], 0, v[60:61]
	v_add_u32_e32 v62, 0x100, v0
	v_mul_u32_u24_e32 v64, 0xaaab, v62
	v_lshrrev_b32_e32 v64, 24, v64
	v_mov_b32_e32 v65, 0
	v_mul_u32_u24_e32 v63, 0x180, v64
	v_sub_u32_e32 v63, v62, v63
	v_add_u32_e32 v66, s62, v64
	v_mov_b64_e32 v[68:69], s[76:77]
	v_mad_i64_i32 v[68:69], s[60:61], v66, s52, v[68:69]
	v_and_b32_e32 v66, 0x7f, v63
	v_lshlrev_b32_e32 v63, 2, v63
	v_and_b32_e32 v63, 0x600, v63
	v_or3_b32 v63, v66, v63, s63
	v_lshlrev_b32_e32 v72, 1, v63
	v_mov_b32_e32 v73, 0
	v_lshl_add_u64 v[68:69], v[68:69], 0, v[72:73]
	global_load_ushort v67, v[68:69], off offset:3072
	v_mov_b64_e32 v[70:71], s[0:1]
	v_lshl_add_u64 v[64:65], v[64:65], 0, s[2:3]
	v_mad_u64_u32 v[70:71], s[60:61], v64, s74, v[70:71]
	v_mad_i32_i24 v71, v65, s74, v71
	v_lshlrev_b32_e32 v72, 2, v63
	v_lshl_add_u64 v[70:71], v[70:71], 0, v[72:73]
	v_add_u32_e32 v74, 0x200, v0
	v_mul_u32_u24_e32 v76, 0xaaab, v74
	v_lshrrev_b32_e32 v76, 24, v76
	v_mov_b32_e32 v77, 0
	v_mul_u32_u24_e32 v75, 0x180, v76
	v_sub_u32_e32 v75, v74, v75
	v_add_u32_e32 v78, s62, v76
	v_mov_b64_e32 v[80:81], s[76:77]
	v_mad_i64_i32 v[80:81], s[60:61], v78, s52, v[80:81]
	v_and_b32_e32 v78, 0x7f, v75
	v_lshlrev_b32_e32 v75, 2, v75
	v_and_b32_e32 v75, 0x600, v75
	v_or3_b32 v75, v78, v75, s63
	v_lshlrev_b32_e32 v84, 1, v75
	v_mov_b32_e32 v85, 0
	v_lshl_add_u64 v[80:81], v[80:81], 0, v[84:85]
	global_load_ushort v79, v[80:81], off offset:3072
	v_mov_b64_e32 v[82:83], s[0:1]
	v_lshl_add_u64 v[76:77], v[76:77], 0, s[2:3]
	v_mad_u64_u32 v[82:83], s[60:61], v76, s74, v[82:83]
	v_mad_i32_i24 v83, v77, s74, v83
	v_lshlrev_b32_e32 v84, 2, v75
	v_lshl_add_u64 v[82:83], v[82:83], 0, v[84:85]
	v_add_u32_e32 v86, 0x300, v0
	v_mul_u32_u24_e32 v88, 0xaaab, v86
	v_lshrrev_b32_e32 v88, 24, v88
	v_mov_b32_e32 v89, 0
	v_mul_u32_u24_e32 v87, 0x180, v88
	v_sub_u32_e32 v87, v86, v87
	v_add_u32_e32 v90, s62, v88
	v_mov_b64_e32 v[92:93], s[76:77]
	v_mad_i64_i32 v[92:93], s[60:61], v90, s52, v[92:93]
	v_and_b32_e32 v90, 0x7f, v87
	v_lshlrev_b32_e32 v87, 2, v87
	v_and_b32_e32 v87, 0x600, v87
	v_or3_b32 v87, v90, v87, s63
	v_lshlrev_b32_e32 v96, 1, v87
	v_mov_b32_e32 v97, 0
	v_lshl_add_u64 v[92:93], v[92:93], 0, v[96:97]
	global_load_ushort v91, v[92:93], off offset:3072
	v_mov_b64_e32 v[94:95], s[0:1]
	v_lshl_add_u64 v[88:89], v[88:89], 0, s[2:3]
	v_mad_u64_u32 v[94:95], s[60:61], v88, s74, v[94:95]
	v_mad_i32_i24 v95, v89, s74, v95
	v_lshlrev_b32_e32 v96, 2, v87
	v_lshl_add_u64 v[94:95], v[94:95], 0, v[96:97]
	s_cmp_lt_u32 s98, 0x800
	s_cbranch_scc0 .Ldqsc_a
	v_add_u32_e32 v98, 0x400, v0
	v_mul_u32_u24_e32 v100, 0xaaab, v98
	v_lshrrev_b32_e32 v100, 24, v100
	v_mov_b32_e32 v101, 0
	v_mul_u32_u24_e32 v99, 0x180, v100
	v_sub_u32_e32 v99, v98, v99
	v_add_u32_e32 v102, s62, v100
	v_mov_b64_e32 v[104:105], s[76:77]
	v_mad_i64_i32 v[104:105], s[60:61], v102, s52, v[104:105]
	v_and_b32_e32 v102, 0x7f, v99
	v_lshlrev_b32_e32 v99, 2, v99
	v_and_b32_e32 v99, 0x600, v99
	v_or3_b32 v99, v102, v99, s63
	v_lshlrev_b32_e32 v108, 1, v99
	v_mov_b32_e32 v109, 0
	v_lshl_add_u64 v[104:105], v[104:105], 0, v[108:109]
	global_load_ushort v103, v[104:105], off offset:3072
	v_mov_b64_e32 v[106:107], s[0:1]
	v_lshl_add_u64 v[100:101], v[100:101], 0, s[2:3]
	v_mad_u64_u32 v[106:107], s[60:61], v100, s74, v[106:107]
	v_mad_i32_i24 v107, v101, s74, v107
	v_lshlrev_b32_e32 v108, 2, v99
	v_lshl_add_u64 v[106:107], v[106:107], 0, v[108:109]
.Ldqsc_a:
	s_waitcnt vmcnt(0)
	v_lshlrev_b32_e32 v55, 16, v55
	global_store_dword v[58:59], v55, off
	v_lshlrev_b32_e32 v67, 16, v67
	global_store_dword v[70:71], v67, off
	v_lshlrev_b32_e32 v79, 16, v79
	global_store_dword v[82:83], v79, off
	v_lshlrev_b32_e32 v91, 16, v91
	global_store_dword v[94:95], v91, off
	s_cmp_lt_u32 s98, 0x800
	s_cbranch_scc0 .Ldqsc_b
	v_lshlrev_b32_e32 v103, 16, v103
	global_store_dword v[106:107], v103, off
.Ldqsc_b:
	s_or_b64 exec, exec, s[54:55]
	v_readlane_b32 s92, v235, 6
	s_lshl_b32 s2, s92, 1
	s_and_b32 s2, s2, -8
	s_addk_i32 s2, 0x4000
	v_or_b32_e32 v6, s2, v164
	v_ashrrev_i32_e32 v7, 31, v6
	v_lshlrev_b64 v[48:49], 10, v[6:7]
	v_or_b32_e32 v6, s2, v166
	v_ashrrev_i32_e32 v7, 31, v6
	v_readlane_b32 s93, v235, 7
	v_lshlrev_b64 v[50:51], 10, v[6:7]
	v_or_b32_e32 v6, s2, v168
	v_readlane_b32 s76, v237, 3
	v_ashrrev_i32_e32 v7, 31, v6
	s_lshl_b64 s[60:61], s[92:93], 16
	v_readlane_b32 s84, v237, 11
	v_lshlrev_b64 v[52:53], 10, v[6:7]
	v_or_b32_e32 v6, s2, v173
	v_readlane_b32 s85, v237, 12
	s_add_u32 s2, s84, s60
	s_addc_u32 s3, s85, s61
	s_lshl_b64 s[54:55], s[92:93], 2
	v_readlane_b32 s62, v237, 63
	v_readlane_b32 s63, v236, 0
	s_add_u32 s52, s62, s54
	s_addc_u32 s55, s63, s55
	s_add_u32 s54, s52, 0xf33d000
	s_addc_u32 s55, s55, 0
	s_lshl_b32 s52, s92, 8
	s_mov_b64 s[62:63], 0x1000
	s_and_b32 s52, s52, 0x300
	v_lshl_add_u64 v[58:59], v[2:3], 0, s[62:63]
	s_mov_b64 s[62:63], 0x2000
	v_ashrrev_i32_e32 v7, 31, v6
	s_add_u32 s60, s67, s60
	v_lshl_add_u64 v[60:61], v[2:3], 0, s[62:63]
	s_mov_b64 s[62:63], 0x3000
	v_mov_b32_e32 v45, v5
	v_lshlrev_b64 v[54:55], 10, v[6:7]
	v_lshl_add_u64 v[56:57], v[42:43], 0, s[52:53]
	s_addc_u32 s61, s68, s61
	v_lshl_add_u64 v[62:63], v[2:3], 0, s[62:63]
	v_lshl_add_u64 v[64:65], s[56:57], 0, v[44:45]
	s_mov_b32 s52, 0
	s_mov_b64 s[56:57], -1
	s_barrier
	v_readlane_b32 s77, v237, 4
	v_readlane_b32 s78, v237, 5
	v_readlane_b32 s79, v237, 6
	v_readlane_b32 s80, v237, 7
	v_readlane_b32 s81, v237, 8
	v_readlane_b32 s82, v237, 9
	v_readlane_b32 s83, v237, 10
	v_readlane_b32 s86, v237, 13
	v_readlane_b32 s87, v237, 14
	v_readlane_b32 s88, v237, 15
	v_readlane_b32 s89, v237, 16
	v_readlane_b32 s90, v237, 17
	v_readlane_b32 s91, v237, 18
	s_branch .LBB0_566
